# ADIFF fast path: the 4 LDS-DMA issues of chunk ch+3 spread over the 4 tail PV pairs of the body instead of one burst after the barrier (address math stays at the barrier)
# speedup vs baseline: 1.0408x; 1.0070x over previous
; #define LAS __attribute__((address_space(3)))
; __device__ __forceinline__ void diff_attn_phase(const Params& p, LAS unsigned char* lds) {
;     ...
;         auto issue = [&](int ch, int stg) {
;             const char* kg = (const char*)(kp + (tokb + 64 * ch) * ld); const char* vg = (const char*)(vp + (tokb + 64 * ch) * ld);
;             LAS unsigned char* sb = lds + stg * STG;
; #pragma unroll
;             for (int i = 0; i < 2; ++i) { unsigned o = doff[i]; asm volatile("" : "+v"(o));
;                 __builtin_amdgcn_global_load_lds((const void*)(kg + o), (LAS void*)(sb + dlds[i]), 16, 0, 0);
;                 __builtin_amdgcn_global_load_lds((const void*)(vg + o), (LAS void*)(sb + 16384 + dlds[i]), 16, 0, 0); }
;         };
;         issue(0, 0); issue(1, 1);
;         int s_cur = 0, s_nn = 2;
;         for (int ch = 0; ch < NCH; ++ch) {
;             if (ch + 1 < NCH) asm volatile("s_waitcnt vmcnt(4)" ::: "memory"); else asm volatile("s_waitcnt vmcnt(0)" ::: "memory");
;             __builtin_amdgcn_s_barrier(); asm volatile("" ::: "memory");
;             if (ch + 2 < NCH) issue(ch + 2, s_nn);
;             const LAS unsigned char* Ksb = lds + s_cur * STG; const LAS unsigned char* Vsb = Ksb + 16384;
;             s_nn = s_cur; s_cur = (s_cur == 2) ? 0 : s_cur + 1;
; #pragma clang loop unroll(disable)
;             for (int u = 0; u < 2; ++u) {
;                 const LAS unsigned char* Ku = Ksb + u * 8192; const LAS unsigned char* Vu = Vsb + u * 8192;
;                 int kxl = kx, vb0l = vb0, vb1l = vb1; asm volatile("" : "+v"(kxl), "+v"(vb0l), "+v"(vb1l));
;                 bf16x8 kf[4];
; #pragma unroll
;                 for (int ks = 0; ks < 4; ++ks) kf[ks] = *(const LAS bf16x8*)(Ku + kbase + (kxl ^ (32 * ks)));
.Lfb_w1F:
	s_barrier
	s_add_i32 s2, s29, 1
	s_and_b32 s2, s2, 3
	s_mov_b32 s37, 0x8000
	s_cmp_eq_u32 s2, 0
	s_cselect_b32 s37, 0xfffe8000, s37
	v_add_u32_e32 v1, s37, v1
	s_add_i32 s2, s29, 3
	s_lshl_b32 s10, s2, 6
	s_add_u32 s10, s26, s10
	s_addc_u32 s11, s27, 0
	s_lshl_b64 s[10:11], s[10:11], 13
	s_add_u32 s42, s25, s10
	s_addc_u32 s43, s28, s11
	s_add_u32 s10, s22, s10
	s_addc_u32 s11, s23, s11
	s_and_b32 s2, s2, 3
	s_lshl_b32 s2, s2, 15
	s_add_i32 s2, s2, s34
	s_waitcnt lgkmcnt(6)
	v_mfma_f32_32x32x16_bf16 v[114:129], v[198:201], v[222:225], v[114:129]
	v_exp_f32_e32 v130, v130
	v_exp_f32_e32 v131, v131
	v_exp_f32_e32 v132, v132
	v_mfma_f32_32x32x16_bf16 v[50:65], v[198:201], v[226:229], v[50:65]
	v_add_u32_e32 v198, v246, v1
	ds_read_b128 v[198:201], v198
	v_exp_f32_e32 v133, v133
	v_add_f32_e32 v212, v212, v130
	v_add_f32_e32 v212, v212, v131
	s_cmpk_gt_u32 s29, 0x7c
	s_cbranch_scc1 .Lfb_nd0F
	s_mov_b32 m0, s2
	s_nop 0
	global_load_lds_dwordx4 v241, s[42:43]
.Lfb_nd0F:
	s_waitcnt lgkmcnt(5)
	v_mfma_f32_32x32x16_bf16 v[98:113], v[202:205], v[222:225], v[98:113]
	v_add_f32_e32 v212, v212, v132
	v_add_f32_e32 v212, v212, v133
	v_exp_f32_e32 v134, v134
	v_mfma_f32_32x32x16_bf16 v[34:49], v[202:205], v[226:229], v[34:49]
	v_xad_u32 v202, v246, 32, v1
	ds_read_b128 v[202:205], v202
	v_exp_f32_e32 v135, v135
	v_exp_f32_e32 v136, v136
	v_exp_f32_e32 v137, v137
	s_cmpk_gt_u32 s29, 0x7c
	s_cbranch_scc1 .Lfb_nd1F
	s_add_i32 s35, s2, 0x4000
	s_mov_b32 m0, s35
	s_nop 0
	global_load_lds_dwordx4 v241, s[10:11]
.Lfb_nd1F:
	s_waitcnt lgkmcnt(4)
	v_mfma_f32_32x32x16_bf16 v[82:97], v[208:211], v[222:225], v[82:97]
	v_add_f32_e32 v212, v212, v134
	v_add_f32_e32 v212, v212, v135
	v_add_f32_e32 v212, v212, v136
	v_mfma_f32_32x32x16_bf16 v[18:33], v[208:211], v[226:229], v[18:33]
	v_xad_u32 v208, v246, 64, v1
	ds_read_b128 v[208:211], v208
	v_add_f32_e32 v212, v212, v137
	v_cvt_pk_bf16_f32 v214, v146, v147
	v_cvt_pk_bf16_f32 v215, v148, v149
	s_cmpk_gt_u32 s29, 0x7c
	s_cbranch_scc1 .Lfb_nd2F
	s_add_i32 s35, s2, 0x2000
	s_mov_b32 m0, s35
	s_nop 0
	global_load_lds_dwordx4 v243, s[42:43]
.Lfb_nd2F:
	s_waitcnt lgkmcnt(3)
	v_mfma_f32_32x32x16_bf16 v[66:81], v[230:233], v[222:225], v[66:81]
	v_cvt_pk_bf16_f32 v216, v150, v151
	v_cvt_pk_bf16_f32 v217, v152, v153
	v_cvt_pk_bf16_f32 v218, v130, v131
	v_cvt_pk_bf16_f32 v219, v132, v133
	v_cvt_pk_bf16_f32 v220, v134, v135
	v_cvt_pk_bf16_f32 v221, v136, v137
	v_cvt_pk_bf16_f32 v222, v154, v155
	v_cvt_pk_bf16_f32 v223, v156, v157
	v_cvt_pk_bf16_f32 v224, v158, v159
	v_cvt_pk_bf16_f32 v225, v160, v161
	v_mfma_f32_32x32x16_bf16 v[2:17], v[230:233], v[226:229], v[2:17]
	v_xad_u32 v230, v246, s47, v1
	ds_read_b128 v[230:233], v230
	s_cmpk_gt_u32 s29, 0x7c
	s_cbranch_scc1 .Lfb_nd3F
	s_add_i32 s35, s2, 0x6000
	s_mov_b32 m0, s35
	s_nop 0
	global_load_lds_dwordx4 v243, s[10:11]
; #define LAS __attribute__((address_space(3)))
; __device__ __forceinline__ void diff_attn_phase(const Params& p, LAS unsigned char* lds) {
;     ...
;                 for (int ks = 0; ks < 4; ++ks) kf[ks] = *(const LAS bf16x8*)(Ku + kbase + (kxl ^ (32 * ks)));
;                 bf16x8 P[2][2];
; #pragma unroll
;                 for (int r = 0; r < 2; ++r) {
;                     f32x16 S;
; #pragma unroll
;                     for (int i = 0; i < 16; ++i) S[i] = 0.f;
; #pragma unroll
;                     for (int ks = 0; ks < 4; ++ks) S = __builtin_amdgcn_mfma_f32_32x32x16_bf16(kf[ks], qf[r][ks], S, 0, 0, 0);
;                     S = __builtin_amdgcn_mfma_f32_32x32x16_bf16(kone, qm[r], S, 0, 0, 0);
; #pragma unroll
;                     for (int i = 0; i < 16; ++i) S[i] = __builtin_amdgcn_exp2f(S[i]);
;                     l[r] += sum16(S);
;                     P[r][0] = pack8(S, 0); P[r][1] = pack8(S, 8);
;                 }
; #pragma unroll
;                 for (int t = 0; t < 4; ++t) {
;                     const LAS unsigned char* a0 = Vu + (vb0l ^ (64 * t)); const LAS unsigned char* a1 = Vu + (vb1l ^ (64 * t));
;                     const bf16x8 v0 = tr_pair(a0, a1), v1 = tr_pair(a0 + 4096, a1 + 4096);
;                     O[0][t] = __builtin_amdgcn_mfma_f32_32x32x16_bf16(v0, P[0][0], O[0][t], 0, 0, 0);
;                     O[1][t] = __builtin_amdgcn_mfma_f32_32x32x16_bf16(v0, P[1][0], O[1][t], 0, 0, 0);
;                     O[0][t] = __builtin_amdgcn_mfma_f32_32x32x16_bf16(v1, P[0][1], O[0][t], 0, 0, 0);
;                     O[1][t] = __builtin_amdgcn_mfma_f32_32x32x16_bf16(v1, P[1][1], O[1][t], 0, 0, 0);
;                 }
.Lfb_nd3F:
	s_waitcnt lgkmcnt(3)
	v_mfma_f32_32x32x16_bf16 v[146:161], v[198:201], v[166:169], 0
	v_exp_f32_e32 v138, v138
	v_exp_f32_e32 v139, v139
	v_exp_f32_e32 v140, v140
	v_exp_f32_e32 v141, v141
	v_add_f32_e32 v212, v212, v138
	s_waitcnt lgkmcnt(2)
	v_mfma_f32_32x32x16_bf16 v[146:161], v[202:205], v[170:173], v[146:161]
	v_add_f32_e32 v212, v212, v139
	v_add_f32_e32 v212, v212, v140
	v_add_f32_e32 v212, v212, v141
	v_exp_f32_e32 v142, v142
	v_exp_f32_e32 v143, v143
	s_waitcnt lgkmcnt(1)
	v_mfma_f32_32x32x16_bf16 v[146:161], v[208:211], v[174:177], v[146:161]
	v_exp_f32_e32 v144, v144
	v_exp_f32_e32 v145, v145
	v_add_f32_e32 v212, v212, v142
	v_add_f32_e32 v212, v212, v143
	v_add_f32_e32 v212, v212, v144
	s_waitcnt lgkmcnt(0)
	v_mfma_f32_32x32x16_bf16 v[146:161], v[230:233], v[178:181], v[146:161]
	v_add_f32_e32 v212, v212, v145
	v_cvt_pk_bf16_f32 v226, v138, v139
	v_cvt_pk_bf16_f32 v227, v140, v141
	v_cvt_pk_bf16_f32 v228, v142, v143
	v_cvt_pk_bf16_f32 v229, v144, v145
	v_mfma_f32_32x32x16_bf16 v[130:145], v[198:201], v[182:185], 0
	ds_read_b64_tr_b16 v[198:199], v234 offset:24576
	ds_read_b64_tr_b16 v[200:201], v235 offset:24576
	v_mfma_f32_32x32x16_bf16 v[130:145], v[202:205], v[186:189], v[130:145]
	ds_read_b64_tr_b16 v[202:203], v237 offset:24576
	ds_read_b64_tr_b16 v[204:205], v236 offset:24576
	v_mfma_f32_32x32x16_bf16 v[130:145], v[208:211], v[190:193], v[130:145]
	ds_read_b64_tr_b16 v[208:209], v238 offset:24576
	ds_read_b64_tr_b16 v[210:211], v239 offset:24576
	v_exp_f32_e32 v146, v146
	v_exp_f32_e32 v147, v147
	v_exp_f32_e32 v148, v148
	v_exp_f32_e32 v149, v149
	v_mfma_f32_32x32x16_bf16 v[130:145], v[230:233], v[194:197], v[130:145]
	ds_read_b64_tr_b16 v[230:231], v250 offset:24576
	ds_read_b64_tr_b16 v[232:233], v251 offset:24576
	v_add_f32_e32 v213, v213, v146
	v_add_f32_e32 v213, v213, v147
	v_add_f32_e32 v213, v213, v148
	v_add_f32_e32 v213, v213, v149
	s_waitcnt lgkmcnt(6)
	v_mfma_f32_32x32x16_bf16 v[114:129], v[198:201], v[214:217], v[114:129]
	v_exp_f32_e32 v150, v150
	v_exp_f32_e32 v151, v151
	v_exp_f32_e32 v152, v152
	v_mfma_f32_32x32x16_bf16 v[50:65], v[198:201], v[218:221], v[50:65]
	ds_read_b64_tr_b16 v[198:199], v234 offset:28672
	ds_read_b64_tr_b16 v[200:201], v235 offset:28672
	v_exp_f32_e32 v153, v153
	v_add_f32_e32 v213, v213, v150
	v_add_f32_e32 v213, v213, v151
	s_waitcnt lgkmcnt(6)
	v_mfma_f32_32x32x16_bf16 v[98:113], v[202:205], v[214:217], v[98:113]
	v_add_f32_e32 v213, v213, v152
	v_add_f32_e32 v213, v213, v153
	v_exp_f32_e32 v154, v154
	v_mfma_f32_32x32x16_bf16 v[34:49], v[202:205], v[218:221], v[34:49]
	ds_read_b64_tr_b16 v[202:203], v237 offset:28672
	ds_read_b64_tr_b16 v[204:205], v236 offset:28672
	v_exp_f32_e32 v155, v155
	v_exp_f32_e32 v156, v156
	v_exp_f32_e32 v157, v157
	s_waitcnt lgkmcnt(6)
	v_mfma_f32_32x32x16_bf16 v[82:97], v[208:211], v[214:217], v[82:97]
	v_add_f32_e32 v213, v213, v154
	v_add_f32_e32 v213, v213, v155
	v_add_f32_e32 v213, v213, v156
	v_mfma_f32_32x32x16_bf16 v[18:33], v[208:211], v[218:221], v[18:33]
	ds_read_b64_tr_b16 v[208:209], v238 offset:28672
	ds_read_b64_tr_b16 v[210:211], v239 offset:28672
	v_add_f32_e32 v213, v213, v157
	v_exp_f32_e32 v158, v158
	v_exp_f32_e32 v159, v159
	s_waitcnt lgkmcnt(6)
	v_mfma_f32_32x32x16_bf16 v[66:81], v[230:233], v[214:217], v[66:81]
	v_exp_f32_e32 v160, v160
	v_exp_f32_e32 v161, v161
	v_add_f32_e32 v213, v213, v158
	v_mfma_f32_32x32x16_bf16 v[2:17], v[230:233], v[218:221], v[2:17]
	ds_read_b64_tr_b16 v[230:231], v250 offset:28672
	ds_read_b64_tr_b16 v[232:233], v251 offset:28672
	v_add_f32_e32 v213, v213, v159
	v_add_f32_e32 v213, v213, v160
	v_add_f32_e32 v213, v213, v161
	v_add_u32_e32 v234, s37, v234
	v_add_u32_e32 v235, s37, v235
	v_add_u32_e32 v237, s37, v237
	v_add_u32_e32 v236, s37, v236
	v_add_u32_e32 v238, s37, v238
	v_add_u32_e32 v239, s37, v239
	v_add_u32_e32 v250, s37, v250
	v_add_u32_e32 v251, s37, v251
	s_waitcnt lgkmcnt(6)
	v_mfma_f32_32x32x16_bf16 v[114:129], v[198:201], v[222:225], v[114:129]
	v_exp_f32_e32 v130, v130
	v_exp_f32_e32 v131, v131
	v_exp_f32_e32 v132, v132
	v_mfma_f32_32x32x16_bf16 v[50:65], v[198:201], v[226:229], v[50:65]
	v_add_u32_e32 v198, v246, v1
	ds_read_b128 v[198:201], v198 offset:8192
	v_exp_f32_e32 v133, v133
	v_add_f32_e32 v212, v212, v130
	v_add_f32_e32 v212, v212, v131
	s_waitcnt lgkmcnt(5)
	v_mfma_f32_32x32x16_bf16 v[98:113], v[202:205], v[222:225], v[98:113]
	v_add_f32_e32 v212, v212, v132
	v_add_f32_e32 v212, v212, v133
	v_exp_f32_e32 v134, v134
	v_mfma_f32_32x32x16_bf16 v[34:49], v[202:205], v[226:229], v[34:49]
	v_xad_u32 v202, v246, 32, v1
	ds_read_b128 v[202:205], v202 offset:8192
	v_exp_f32_e32 v135, v135
	v_exp_f32_e32 v136, v136
	v_exp_f32_e32 v137, v137
	s_waitcnt lgkmcnt(4)
	v_mfma_f32_32x32x16_bf16 v[82:97], v[208:211], v[222:225], v[82:97]
	v_add_f32_e32 v212, v212, v134
	v_add_f32_e32 v212, v212, v135
	v_add_f32_e32 v212, v212, v136
	v_mfma_f32_32x32x16_bf16 v[18:33], v[208:211], v[226:229], v[18:33]
	v_xad_u32 v208, v246, 64, v1
	ds_read_b128 v[208:211], v208 offset:8192
	v_add_f32_e32 v212, v212, v137
	v_cvt_pk_bf16_f32 v214, v146, v147
	v_cvt_pk_bf16_f32 v215, v148, v149
	s_waitcnt lgkmcnt(3)
	v_mfma_f32_32x32x16_bf16 v[66:81], v[230:233], v[222:225], v[66:81]
	v_cvt_pk_bf16_f32 v216, v150, v151
	v_cvt_pk_bf16_f32 v217, v152, v153
	v_cvt_pk_bf16_f32 v218, v130, v131
	v_cvt_pk_bf16_f32 v219, v132, v133
	v_cvt_pk_bf16_f32 v220, v134, v135
	v_cvt_pk_bf16_f32 v221, v136, v137
	v_cvt_pk_bf16_f32 v222, v154, v155
	v_cvt_pk_bf16_f32 v223, v156, v157
	v_cvt_pk_bf16_f32 v224, v158, v159
	v_cvt_pk_bf16_f32 v225, v160, v161
	v_mfma_f32_32x32x16_bf16 v[2:17], v[230:233], v[226:229], v[2:17]
	v_xad_u32 v230, v246, s47, v1
	ds_read_b128 v[230:233], v230 offset:8192
	s_add_i32 s29, s29, 1
	s_branch .Lfb_loopF
